# p1: de-staggered tile epilogue - extra barrier pair so both wave groups run cvt+stores concurrently instead of one after the other
# speedup vs baseline: 1.0007x; 1.0007x over previous
; #define PG8_STAGE(bufoff, gbase, voff) do { _Pragma("unroll") for (int _i = 0; _i < 2; ++_i) \
;         __builtin_amdgcn_global_load_lds((const unsigned*)((const char*)(gbase) + (voff)[_i]), (LAS unsigned*)(lds + (bufoff) + ldsw + _i * 8192), 16, 0, 0); } while (0)
; #define PG8_LDA(dst, b, h) do { _Pragma("unroll") for (int m = 0; m < 4; ++m) _Pragma("unroll") for (int k = 0; k < 2; ++k) dst[m][k] = *(const LAS bf16x8*)(lds + PG8_SA(b, h) + aoff + m * 2048 + k * 1024); } while (0)
; #define PG8_LDB(dst, b, h) do { _Pragma("unroll") for (int n = 0; n < 2; ++n) _Pragma("unroll") for (int k = 0; k < 2; ++k) dst[n][k] = *(const LAS bf16x8*)(lds + PG8_SB(b, h) + boff + n * 2048 + k * 1024); } while (0)
; #define PG8_MMA(ai, bj, At, Bt) do { __builtin_amdgcn_s_setprio(1); _Pragma("unroll") for (int m = 0; m < 4; ++m) _Pragma("unroll") for (int n = 0; n < 2; ++n) _Pragma("unroll") for (int k = 0; k < 2; ++k) \
;         acc[ai][bj][m][n] = __builtin_amdgcn_mfma_f32_16x16x32_bf16(Bt[n][k], At[m][k], acc[ai][bj][m][n], 0, 0, 0); __builtin_amdgcn_s_setprio(0); } while (0)
; #define PG8_WAIT_V(n) asm volatile("s_waitcnt vmcnt(" #n ")" ::: "memory")
; template <class Epi>
; DI void gemm_phase(LAS unsigned char* lds, const Gemm g, const StaticOrder& S, const Epi& E) {
;     ...
;         for (int t = 0; t < nt; t += 2) {
;             const bool last = (t == nt - 2);
;             const char* a1 = cA + (size_t)(t + 1) * kstep;
;             const char* a2 = last ? nA : cA + (size_t)(t + 2) * kstep; const char* b2 = last ? nB : cB + (size_t)(t + 2) * kstep;
;             const char* a3 = a2 + kstep; const char* b3 = b2 + kstep;
;             if constexpr (Epi::HAS_MID) { if (t == Epi::MID_T) E.mid(acc, cur, wr, wc, fr, fq); }
;             PG8_LDB(B0, 0, 0); PG8_SCHED; PG8_LDA(At, 0, 0); PG8_STAGE(PG8_SA(1, 1), a1 + hstepA, voffA);
;             PG8_WAIT_L(8); PG8_BAR; PG8_WAIT_L(0); PG8_MMA(0, 0, At, B0); PG8_BAR; PG8_SCHED;
;             PG8_LDB(B1, 0, 1); PG8_STAGE(PG8_SB(0, 0), b2, voffB);
;             PG8_BAR; PG8_WAIT_L(0); PG8_MMA(0, 1, At, B1); PG8_BAR;
;             PG8_LDA(At, 0, 1); PG8_STAGE(PG8_SA(0, 0), a2, voffA);
;             PG8_BAR; PG8_WAIT_L(0); PG8_MMA(1, 0, At, B0); PG8_BAR; PG8_SCHED;
;             PG8_STAGE(PG8_SB(0, 1), b2 + hstepB, voffB);
;             PG8_WAIT_V(6); PG8_BAR; PG8_MMA(1, 1, At, B1); PG8_BAR;
.LBB0_113:
	ds_read_b128 v[150:153], v147
	ds_read_b128 v[154:157], v147 offset:1024
	ds_read_b128 v[158:161], v147 offset:2048
	ds_read_b128 v[162:165], v147 offset:3072
	s_add_u32 s0, s52, 0xfff80080
	s_addc_u32 s1, s53, -1
	s_cmp_eq_u32 s83, 28
	s_cselect_b32 s57, s47, s1
	s_cselect_b32 s56, s79, s0
	s_cselect_b32 s55, s17, s82
	s_cselect_b32 s54, s80, s81
	ds_read_b128 v[166:169], v148
	ds_read_b128 v[174:177], v148 offset:1024
	ds_read_b128 v[178:181], v148 offset:2048
	ds_read_b128 v[182:185], v148 offset:3072
	ds_read_b128 v[186:189], v148 offset:4096
	ds_read_b128 v[190:193], v148 offset:5120
	ds_read_b128 v[194:197], v148 offset:6144
	ds_read_b128 v[198:201], v148 offset:7168
	s_waitcnt lgkmcnt(11)
	ds_read_b128 v[202:205], v149
	ds_read_b128 v[206:209], v149 offset:1024
	ds_read_b128 v[210:213], v149 offset:2048
	ds_read_b128 v[216:219], v149 offset:3072
	v_lshl_add_u64 v[238:239], s[52:53], 0, v[136:137]
	s_add_i32 m0, s9, 0xc000
	s_nop 0
	global_load_lds_dwordx4 v[238:239], off
	v_lshl_add_u64 v[238:239], s[52:53], 0, v[138:139]
	s_add_i32 m0, s9, 0xe000
	s_nop 0
	global_load_lds_dwordx4 v[238:239], off
	s_waitcnt lgkmcnt(0)
	s_waitcnt vmcnt(8)
	s_barrier
	v_mfma_f32_16x16x32_bf16 v[124:127], v[150:153], v[166:169], v[124:127]
	v_mfma_f32_16x16x32_bf16 v[120:123], v[158:161], v[166:169], v[120:123]
	v_mfma_f32_16x16x32_bf16 v[116:119], v[150:153], v[178:181], v[116:119]
	v_mfma_f32_16x16x32_bf16 v[112:115], v[158:161], v[178:181], v[112:115]
	v_mfma_f32_16x16x32_bf16 v[100:103], v[150:153], v[186:189], v[100:103]
	v_mfma_f32_16x16x32_bf16 v[96:99], v[158:161], v[186:189], v[96:99]
	v_mfma_f32_16x16x32_bf16 v[84:87], v[150:153], v[194:197], v[84:87]
	v_mfma_f32_16x16x32_bf16 v[80:83], v[158:161], v[194:197], v[80:83]
	v_mfma_f32_16x16x32_bf16 v[124:127], v[154:157], v[174:177], v[124:127]
	v_mfma_f32_16x16x32_bf16 v[120:123], v[162:165], v[174:177], v[120:123]
	v_mfma_f32_16x16x32_bf16 v[116:119], v[154:157], v[182:185], v[116:119]
	v_mfma_f32_16x16x32_bf16 v[112:115], v[162:165], v[182:185], v[112:115]
	v_mfma_f32_16x16x32_bf16 v[100:103], v[154:157], v[190:193], v[100:103]
	v_mfma_f32_16x16x32_bf16 v[96:99], v[162:165], v[190:193], v[96:99]
	v_mfma_f32_16x16x32_bf16 v[84:87], v[154:157], v[198:201], v[84:87]
	v_mfma_f32_16x16x32_bf16 v[80:83], v[162:165], v[198:201], v[80:83]
	v_mfma_f32_16x16x32_bf16 v[108:111], v[202:205], v[166:169], v[108:111]
	v_mfma_f32_16x16x32_bf16 v[104:107], v[210:213], v[166:169], v[104:107]
	v_mfma_f32_16x16x32_bf16 v[92:95], v[202:205], v[178:181], v[92:95]
	v_mfma_f32_16x16x32_bf16 v[88:91], v[210:213], v[178:181], v[88:91]
	v_mfma_f32_16x16x32_bf16 v[76:79], v[202:205], v[186:189], v[76:79]
	v_mfma_f32_16x16x32_bf16 v[72:75], v[210:213], v[186:189], v[72:75]
	v_mfma_f32_16x16x32_bf16 v[68:71], v[202:205], v[194:197], v[68:71]
	v_mfma_f32_16x16x32_bf16 v[64:67], v[210:213], v[194:197], v[64:67]
	v_mfma_f32_16x16x32_bf16 v[108:111], v[206:209], v[174:177], v[108:111]
	v_mfma_f32_16x16x32_bf16 v[104:107], v[216:219], v[174:177], v[104:107]
	v_mfma_f32_16x16x32_bf16 v[92:95], v[206:209], v[182:185], v[92:95]
	v_mfma_f32_16x16x32_bf16 v[88:91], v[216:219], v[182:185], v[88:91]
	v_mfma_f32_16x16x32_bf16 v[76:79], v[206:209], v[190:193], v[76:79]
	v_mfma_f32_16x16x32_bf16 v[72:75], v[216:219], v[190:193], v[72:75]
	v_mfma_f32_16x16x32_bf16 v[68:71], v[206:209], v[198:201], v[68:71]
	v_mfma_f32_16x16x32_bf16 v[64:67], v[216:219], v[198:201], v[64:67]
	s_barrier
	ds_read_b128 v[166:169], v148 offset:16384
	ds_read_b128 v[174:177], v148 offset:17408
	ds_read_b128 v[178:181], v148 offset:18432
	ds_read_b128 v[182:185], v148 offset:19456
	ds_read_b128 v[186:189], v148 offset:20480
	ds_read_b128 v[190:193], v148 offset:21504
	ds_read_b128 v[194:197], v148 offset:22528
	ds_read_b128 v[198:201], v148 offset:23552
	s_add_i32 s0, s75, s58
	v_lshl_add_u64 v[170:171], s[54:55], 0, v[132:133]
	s_mov_b32 m0, s0
	s_nop 0
	global_load_lds_dwordx4 v[170:171], off
	v_lshl_add_u64 v[220:221], s[54:55], 0, v[128:129]
	s_add_i32 m0, s0, 0x2000
	s_nop 0
	global_load_lds_dwordx4 v[220:221], off
	v_lshl_add_u64 v[222:223], s[56:57], 0, v[134:135]
	s_mov_b32 m0, s9
	s_nop 0
	global_load_lds_dwordx4 v[222:223], off
	v_lshl_add_u64 v[224:225], s[56:57], 0, v[130:131]
	s_mov_b32 m0, s61
	s_nop 0
	global_load_lds_dwordx4 v[224:225], off
	s_add_u32 s0, s54, 0x80000
	s_addc_u32 s1, s55, 0
	s_add_i32 s84, s76, s58
	v_lshl_add_u64 v[238:239], s[0:1], 0, v[132:133]
	s_mov_b32 m0, s84
	s_nop 0
	global_load_lds_dwordx4 v[238:239], off
	v_lshl_add_u64 v[238:239], s[0:1], 0, v[128:129]
	s_add_i32 m0, s84, 0x2000
	s_nop 0
	global_load_lds_dwordx4 v[238:239], off
	s_waitcnt lgkmcnt(0)
	s_waitcnt vmcnt(8)
	s_barrier
; #define PG8_STAGE(bufoff, gbase, voff) do { _Pragma("unroll") for (int _i = 0; _i < 2; ++_i) \
;         __builtin_amdgcn_global_load_lds((const unsigned*)((const char*)(gbase) + (voff)[_i]), (LAS unsigned*)(lds + (bufoff) + ldsw + _i * 8192), 16, 0, 0); } while (0)
; #define PG8_LDA(dst, b, h) do { _Pragma("unroll") for (int m = 0; m < 4; ++m) _Pragma("unroll") for (int k = 0; k < 2; ++k) dst[m][k] = *(const LAS bf16x8*)(lds + PG8_SA(b, h) + aoff + m * 2048 + k * 1024); } while (0)
; #define PG8_LDB(dst, b, h) do { _Pragma("unroll") for (int n = 0; n < 2; ++n) _Pragma("unroll") for (int k = 0; k < 2; ++k) dst[n][k] = *(const LAS bf16x8*)(lds + PG8_SB(b, h) + boff + n * 2048 + k * 1024); } while (0)
; #define PG8_MMA(ai, bj, At, Bt) do { __builtin_amdgcn_s_setprio(1); _Pragma("unroll") for (int m = 0; m < 4; ++m) _Pragma("unroll") for (int n = 0; n < 2; ++n) _Pragma("unroll") for (int k = 0; k < 2; ++k) \
;         acc[ai][bj][m][n] = __builtin_amdgcn_mfma_f32_16x16x32_bf16(Bt[n][k], At[m][k], acc[ai][bj][m][n], 0, 0, 0); __builtin_amdgcn_s_setprio(0); } while (0)
; #define PG8_WAIT_V(n) asm volatile("s_waitcnt vmcnt(" #n ")" ::: "memory")
; #define PG8_WAIT_L(n) asm volatile("s_waitcnt lgkmcnt(" #n ")" ::: "memory")
; #define PG8_BAR __builtin_amdgcn_s_barrier()
; #define PG8_SCHED __builtin_amdgcn_sched_barrier(0)
; template <class Epi>
; DI void gemm_phase(LAS unsigned char* lds, const Gemm g, const StaticOrder& S, const Epi& E) {
;     ...
;             PG8_BAR; PG8_WAIT_L(0); PG8_MMA(1, 0, At, B0); PG8_BAR; PG8_SCHED;
;             PG8_STAGE(PG8_SB(0, 1), b2 + hstepB, voffB);
;             PG8_WAIT_V(6); PG8_BAR; PG8_MMA(1, 1, At, B1); PG8_BAR;
;             PG8_LDB(B0, 1, 0); PG8_SCHED; PG8_LDA(At, 1, 0); PG8_STAGE(PG8_SA(0, 1), a2 + hstepA, voffA);
;             PG8_WAIT_L(8); PG8_BAR; PG8_WAIT_L(0); PG8_MMA(0, 0, At, B0); PG8_BAR; PG8_SCHED;
;             PG8_LDB(B1, 1, 1); PG8_STAGE(PG8_SB(1, 0), b3, voffB);
;             PG8_BAR; PG8_WAIT_L(0); PG8_MMA(0, 1, At, B1); PG8_BAR;
	v_mfma_f32_16x16x32_bf16 v[60:63], v[150:153], v[166:169], v[60:63]
	v_mfma_f32_16x16x32_bf16 v[56:59], v[158:161], v[166:169], v[56:59]
	v_mfma_f32_16x16x32_bf16 v[52:55], v[150:153], v[178:181], v[52:55]
	v_mfma_f32_16x16x32_bf16 v[48:51], v[158:161], v[178:181], v[48:51]
	v_mfma_f32_16x16x32_bf16 v[36:39], v[150:153], v[186:189], v[36:39]
	v_mfma_f32_16x16x32_bf16 v[32:35], v[158:161], v[186:189], v[32:35]
	v_mfma_f32_16x16x32_bf16 v[20:23], v[150:153], v[194:197], v[20:23]
	v_mfma_f32_16x16x32_bf16 v[16:19], v[158:161], v[194:197], v[16:19]
	v_mfma_f32_16x16x32_bf16 v[60:63], v[154:157], v[174:177], v[60:63]
	v_mfma_f32_16x16x32_bf16 v[56:59], v[162:165], v[174:177], v[56:59]
	v_mfma_f32_16x16x32_bf16 v[52:55], v[154:157], v[182:185], v[52:55]
	v_mfma_f32_16x16x32_bf16 v[48:51], v[162:165], v[182:185], v[48:51]
	v_mfma_f32_16x16x32_bf16 v[36:39], v[154:157], v[190:193], v[36:39]
	v_mfma_f32_16x16x32_bf16 v[32:35], v[162:165], v[190:193], v[32:35]
	v_mfma_f32_16x16x32_bf16 v[20:23], v[154:157], v[198:201], v[20:23]
	v_mfma_f32_16x16x32_bf16 v[16:19], v[162:165], v[198:201], v[16:19]
	v_mfma_f32_16x16x32_bf16 v[44:47], v[202:205], v[166:169], v[44:47]
	v_mfma_f32_16x16x32_bf16 v[40:43], v[210:213], v[166:169], v[40:43]
	v_mfma_f32_16x16x32_bf16 v[28:31], v[202:205], v[178:181], v[28:31]
	v_mfma_f32_16x16x32_bf16 v[24:27], v[210:213], v[178:181], v[24:27]
	v_mfma_f32_16x16x32_bf16 v[12:15], v[202:205], v[186:189], v[12:15]
	v_mfma_f32_16x16x32_bf16 v[8:11], v[210:213], v[186:189], v[8:11]
	v_mfma_f32_16x16x32_bf16 v[4:7], v[202:205], v[194:197], v[4:7]
	v_mfma_f32_16x16x32_bf16 v[0:3], v[210:213], v[194:197], v[0:3]
	v_mfma_f32_16x16x32_bf16 v[44:47], v[206:209], v[174:177], v[44:47]
	v_mfma_f32_16x16x32_bf16 v[40:43], v[216:219], v[174:177], v[40:43]
	v_mfma_f32_16x16x32_bf16 v[28:31], v[206:209], v[182:185], v[28:31]
	v_mfma_f32_16x16x32_bf16 v[24:27], v[216:219], v[182:185], v[24:27]
	v_mfma_f32_16x16x32_bf16 v[12:15], v[206:209], v[190:193], v[12:15]
	v_mfma_f32_16x16x32_bf16 v[8:11], v[216:219], v[190:193], v[8:11]
	v_mfma_f32_16x16x32_bf16 v[4:7], v[206:209], v[198:201], v[4:7]
	v_mfma_f32_16x16x32_bf16 v[0:3], v[216:219], v[198:201], v[0:3]
	s_barrier
	v_add_u32_e32 v252, 0x18000, v145
	v_add_u32_e32 v172, 0x1c000, v145
	ds_read_b128 v[150:153], v252
	ds_read_b128 v[154:157], v252 offset:1024
	ds_read_b128 v[158:161], v252 offset:2048
	ds_read_b128 v[162:165], v252 offset:3072
	ds_read_b128 v[166:169], v148 offset:32768
	ds_read_b128 v[174:177], v148 offset:33792
	ds_read_b128 v[178:181], v148 offset:34816
	ds_read_b128 v[182:185], v148 offset:35840
	ds_read_b128 v[186:189], v148 offset:36864
	ds_read_b128 v[190:193], v148 offset:37888
	ds_read_b128 v[194:197], v148 offset:38912
	ds_read_b128 v[198:201], v148 offset:39936
	s_waitcnt lgkmcnt(11)
	ds_read_b128 v[202:205], v172
	ds_read_b128 v[206:209], v172 offset:1024
	ds_read_b128 v[210:213], v172 offset:2048
	ds_read_b128 v[216:219], v172 offset:3072
	s_add_u32 s0, s56, 0x80000
	s_addc_u32 s1, s57, 0
	v_lshl_add_u64 v[238:239], s[0:1], 0, v[134:135]
	s_mov_b32 m0, s68
	s_nop 0
	global_load_lds_dwordx4 v[238:239], off
	v_lshl_add_u64 v[238:239], s[0:1], 0, v[130:131]
	s_mov_b32 m0, s69
	s_nop 0
	global_load_lds_dwordx4 v[238:239], off
	s_waitcnt lgkmcnt(0)
	s_waitcnt vmcnt(8)
	s_barrier
	v_mfma_f32_16x16x32_bf16 v[124:127], v[150:153], v[166:169], v[124:127]
	v_mfma_f32_16x16x32_bf16 v[120:123], v[158:161], v[166:169], v[120:123]
	v_mfma_f32_16x16x32_bf16 v[116:119], v[150:153], v[178:181], v[116:119]
	v_mfma_f32_16x16x32_bf16 v[112:115], v[158:161], v[178:181], v[112:115]
	v_mfma_f32_16x16x32_bf16 v[100:103], v[150:153], v[186:189], v[100:103]
	v_mfma_f32_16x16x32_bf16 v[96:99], v[158:161], v[186:189], v[96:99]
	v_mfma_f32_16x16x32_bf16 v[84:87], v[150:153], v[194:197], v[84:87]
	v_mfma_f32_16x16x32_bf16 v[80:83], v[158:161], v[194:197], v[80:83]
	v_mfma_f32_16x16x32_bf16 v[124:127], v[154:157], v[174:177], v[124:127]
	v_mfma_f32_16x16x32_bf16 v[120:123], v[162:165], v[174:177], v[120:123]
	v_mfma_f32_16x16x32_bf16 v[116:119], v[154:157], v[182:185], v[116:119]
	v_mfma_f32_16x16x32_bf16 v[112:115], v[162:165], v[182:185], v[112:115]
	v_mfma_f32_16x16x32_bf16 v[100:103], v[154:157], v[190:193], v[100:103]
	v_mfma_f32_16x16x32_bf16 v[96:99], v[162:165], v[190:193], v[96:99]
	v_mfma_f32_16x16x32_bf16 v[84:87], v[154:157], v[198:201], v[84:87]
	v_mfma_f32_16x16x32_bf16 v[80:83], v[162:165], v[198:201], v[80:83]
	v_mfma_f32_16x16x32_bf16 v[108:111], v[202:205], v[166:169], v[108:111]
	v_mfma_f32_16x16x32_bf16 v[104:107], v[210:213], v[166:169], v[104:107]
	v_mfma_f32_16x16x32_bf16 v[92:95], v[202:205], v[178:181], v[92:95]
	v_mfma_f32_16x16x32_bf16 v[88:91], v[210:213], v[178:181], v[88:91]
	v_mfma_f32_16x16x32_bf16 v[76:79], v[202:205], v[186:189], v[76:79]
	v_mfma_f32_16x16x32_bf16 v[72:75], v[210:213], v[186:189], v[72:75]
	v_mfma_f32_16x16x32_bf16 v[68:71], v[202:205], v[194:197], v[68:71]
	v_mfma_f32_16x16x32_bf16 v[64:67], v[210:213], v[194:197], v[64:67]
	v_mfma_f32_16x16x32_bf16 v[108:111], v[206:209], v[174:177], v[108:111]
	v_mfma_f32_16x16x32_bf16 v[104:107], v[216:219], v[174:177], v[104:107]
	v_mfma_f32_16x16x32_bf16 v[92:95], v[206:209], v[182:185], v[92:95]
	v_mfma_f32_16x16x32_bf16 v[88:91], v[216:219], v[182:185], v[88:91]
	v_mfma_f32_16x16x32_bf16 v[76:79], v[206:209], v[190:193], v[76:79]
	v_mfma_f32_16x16x32_bf16 v[72:75], v[216:219], v[190:193], v[72:75]
	v_mfma_f32_16x16x32_bf16 v[68:71], v[206:209], v[198:201], v[68:71]
	v_mfma_f32_16x16x32_bf16 v[64:67], v[216:219], v[198:201], v[64:67]
	s_barrier
; #define PG8_STAGE(bufoff, gbase, voff) do { _Pragma("unroll") for (int _i = 0; _i < 2; ++_i) \
;         __builtin_amdgcn_global_load_lds((const unsigned*)((const char*)(gbase) + (voff)[_i]), (LAS unsigned*)(lds + (bufoff) + ldsw + _i * 8192), 16, 0, 0); } while (0)
; #define PG8_LDA(dst, b, h) do { _Pragma("unroll") for (int m = 0; m < 4; ++m) _Pragma("unroll") for (int k = 0; k < 2; ++k) dst[m][k] = *(const LAS bf16x8*)(lds + PG8_SA(b, h) + aoff + m * 2048 + k * 1024); } while (0)
; #define PG8_LDB(dst, b, h) do { _Pragma("unroll") for (int n = 0; n < 2; ++n) _Pragma("unroll") for (int k = 0; k < 2; ++k) dst[n][k] = *(const LAS bf16x8*)(lds + PG8_SB(b, h) + boff + n * 2048 + k * 1024); } while (0)
; #define PG8_MMA(ai, bj, At, Bt) do { __builtin_amdgcn_s_setprio(1); _Pragma("unroll") for (int m = 0; m < 4; ++m) _Pragma("unroll") for (int n = 0; n < 2; ++n) _Pragma("unroll") for (int k = 0; k < 2; ++k) \
;         acc[ai][bj][m][n] = __builtin_amdgcn_mfma_f32_16x16x32_bf16(Bt[n][k], At[m][k], acc[ai][bj][m][n], 0, 0, 0); __builtin_amdgcn_s_setprio(0); } while (0)
; #define PG8_WAIT_V(n) asm volatile("s_waitcnt vmcnt(" #n ")" ::: "memory")
; #define PG8_WAIT_L(n) asm volatile("s_waitcnt lgkmcnt(" #n ")" ::: "memory")
; #define PG8_BAR __builtin_amdgcn_s_barrier()
; #define PG8_SCHED __builtin_amdgcn_sched_barrier(0)
; template <class Epi>
; DI void gemm_phase(LAS unsigned char* lds, const Gemm g, const StaticOrder& S, const Epi& E) {
;     ...
;             PG8_LDB(B1, 1, 1); PG8_STAGE(PG8_SB(1, 0), b3, voffB);
;             PG8_BAR; PG8_WAIT_L(0); PG8_MMA(0, 1, At, B1); PG8_BAR;
;             PG8_LDA(At, 1, 1); PG8_STAGE(PG8_SA(1, 0), a3, voffA);
;             PG8_BAR; PG8_WAIT_L(0); PG8_MMA(1, 0, At, B0); PG8_BAR; PG8_SCHED;
;             PG8_STAGE(PG8_SB(1, 1), b3 + hstepB, voffB);
;             PG8_WAIT_V(6); PG8_BAR; PG8_MMA(1, 1, At, B1); PG8_BAR;
;         }
;         E(acc, cur, wr, wc, fr, fq);
	ds_read_b128 v[166:169], v148 offset:49152
	ds_read_b128 v[174:177], v148 offset:50176
	ds_read_b128 v[178:181], v148 offset:51200
	ds_read_b128 v[182:185], v148 offset:52224
	ds_read_b128 v[186:189], v148 offset:53248
	ds_read_b128 v[190:193], v148 offset:54272
	ds_read_b128 v[194:197], v148 offset:55296
	ds_read_b128 v[198:201], v148 offset:56320
	s_add_i32 s0, s58, 0x18000
	v_lshl_add_u64 v[238:239], v[170:171], 0, s[4:5]
	s_mov_b32 m0, s0
	s_nop 0
	global_load_lds_dwordx4 v[238:239], off
	v_lshl_add_u64 v[238:239], v[220:221], 0, s[4:5]
	s_add_i32 m0, s0, 0x2000
	s_nop 0
	global_load_lds_dwordx4 v[238:239], off
	v_lshl_add_u64 v[238:239], v[222:223], 0, s[4:5]
	s_mov_b32 m0, s71
	s_nop 0
	global_load_lds_dwordx4 v[238:239], off
	v_lshl_add_u64 v[238:239], v[224:225], 0, s[4:5]
	s_mov_b32 m0, s72
	s_nop 0
	global_load_lds_dwordx4 v[238:239], off
	s_add_u32 s0, s54, 0x80080
	s_addc_u32 s1, s55, 0
	s_add_i32 s84, s58, 0x1c000
	v_lshl_add_u64 v[238:239], s[0:1], 0, v[132:133]
	s_mov_b32 m0, s84
	s_nop 0
	global_load_lds_dwordx4 v[238:239], off
	v_lshl_add_u64 v[238:239], s[0:1], 0, v[128:129]
	s_add_i32 m0, s84, 0x2000
	s_nop 0
	global_load_lds_dwordx4 v[238:239], off
	s_waitcnt lgkmcnt(0)
	s_waitcnt vmcnt(8)
	s_add_i32 s83, s83, 2
	s_add_u32 s52, s52, 0x100
	s_addc_u32 s53, s53, 0
	s_add_u32 s81, s81, 0x100
	s_addc_u32 s82, s82, 0
	s_cmp_gt_u32 s83, 29
	s_barrier
	v_mfma_f32_16x16x32_bf16 v[60:63], v[150:153], v[166:169], v[60:63]
	v_mfma_f32_16x16x32_bf16 v[56:59], v[158:161], v[166:169], v[56:59]
	v_mfma_f32_16x16x32_bf16 v[52:55], v[150:153], v[178:181], v[52:55]
	v_mfma_f32_16x16x32_bf16 v[48:51], v[158:161], v[178:181], v[48:51]
	v_mfma_f32_16x16x32_bf16 v[36:39], v[150:153], v[186:189], v[36:39]
	v_mfma_f32_16x16x32_bf16 v[32:35], v[158:161], v[186:189], v[32:35]
	v_mfma_f32_16x16x32_bf16 v[20:23], v[150:153], v[194:197], v[20:23]
	v_mfma_f32_16x16x32_bf16 v[16:19], v[158:161], v[194:197], v[16:19]
	v_mfma_f32_16x16x32_bf16 v[60:63], v[154:157], v[174:177], v[60:63]
	v_mfma_f32_16x16x32_bf16 v[56:59], v[162:165], v[174:177], v[56:59]
	v_mfma_f32_16x16x32_bf16 v[52:55], v[154:157], v[182:185], v[52:55]
	v_mfma_f32_16x16x32_bf16 v[48:51], v[162:165], v[182:185], v[48:51]
	v_mfma_f32_16x16x32_bf16 v[36:39], v[154:157], v[190:193], v[36:39]
	v_mfma_f32_16x16x32_bf16 v[32:35], v[162:165], v[190:193], v[32:35]
	v_mfma_f32_16x16x32_bf16 v[20:23], v[154:157], v[198:201], v[20:23]
	v_mfma_f32_16x16x32_bf16 v[16:19], v[162:165], v[198:201], v[16:19]
	v_mfma_f32_16x16x32_bf16 v[44:47], v[202:205], v[166:169], v[44:47]
	v_mfma_f32_16x16x32_bf16 v[40:43], v[210:213], v[166:169], v[40:43]
	v_mfma_f32_16x16x32_bf16 v[28:31], v[202:205], v[178:181], v[28:31]
	v_mfma_f32_16x16x32_bf16 v[24:27], v[210:213], v[178:181], v[24:27]
	v_mfma_f32_16x16x32_bf16 v[12:15], v[202:205], v[186:189], v[12:15]
	v_mfma_f32_16x16x32_bf16 v[8:11], v[210:213], v[186:189], v[8:11]
	v_mfma_f32_16x16x32_bf16 v[4:7], v[202:205], v[194:197], v[4:7]
	v_mfma_f32_16x16x32_bf16 v[0:3], v[210:213], v[194:197], v[0:3]
	v_mfma_f32_16x16x32_bf16 v[44:47], v[206:209], v[174:177], v[44:47]
	v_mfma_f32_16x16x32_bf16 v[40:43], v[216:219], v[174:177], v[40:43]
	v_mfma_f32_16x16x32_bf16 v[28:31], v[206:209], v[182:185], v[28:31]
	v_mfma_f32_16x16x32_bf16 v[24:27], v[216:219], v[182:185], v[24:27]
	v_mfma_f32_16x16x32_bf16 v[12:15], v[206:209], v[190:193], v[12:15]
	v_mfma_f32_16x16x32_bf16 v[8:11], v[216:219], v[190:193], v[8:11]
	v_mfma_f32_16x16x32_bf16 v[4:7], v[206:209], v[198:201], v[4:7]
	v_mfma_f32_16x16x32_bf16 v[0:3], v[216:219], v[198:201], v[0:3]
	s_barrier
	s_cbranch_scc0 .LBB0_113
	s_cmpk_gt_u32 s33, 0xff
	s_cbranch_scc1 .Lp1_e0
	s_barrier
; DI unsigned pk2(float lo, float hi) { f32x2 v = {lo, hi}; bf16x2_t b = __builtin_convertvector(v, bf16x2_t); return __builtin_bit_cast(unsigned, b); }
; #define PG8_WAIT_V(n) asm volatile("s_waitcnt vmcnt(" #n ")" ::: "memory")
; #define PG8_BAR __builtin_amdgcn_s_barrier()
; template <class Epi>
; DI void gemm_phase(LAS unsigned char* lds, const Gemm g, const StaticOrder& S, const Epi& E) {
;     ...
;         E(acc, cur, wr, wc, fr, fq);
;         if (!has_next) break;
; #pragma unroll
;         for (int a = 0; a < 2; ++a)
; #pragma unroll
;             for (int b = 0; b < 2; ++b)
; #pragma unroll
;                 for (int m = 0; m < 4; ++m)
; #pragma unroll
;                     for (int n = 0; n < 2; ++n) acc[a][b][m][n] = (f32x4){0.f, 0.f, 0.f, 0.f};
;         cur = nxt; cA = nA; cB = nB; ++ui;
;     }
;     PG8_WAIT_V(0);
;     if (wr == 0) PG8_BAR;
;     PG8_BAR;
;     DI void operator()(const f32x4 (&acc)[2][2][4][2], const Unit& u, int wr, int wc, int fr, int fq) const {
;         const int row0 = u.pm * BM + wr * 64 + fr, col0 = u.pn * BM + wc * 32 + 8 * fq;
; #pragma unroll
;         for (int ai = 0; ai < 2; ++ai)
; #pragma unroll
;             for (int m = 0; m < 4; ++m) { bf16_t* rowp = O + (size_t)(row0 + ai * HALF + m * 16) * ldc + col0;
; #pragma unroll
;                 for (int bj = 0; bj < 2; ++bj) { const f32x4 v0 = acc[ai][bj][m][0], v1 = acc[ai][bj][m][1];
;                     u32x4 w; w.x = pk2(v0[0], v0[1]); w.y = pk2(v0[2], v0[3]); w.z = pk2(v1[0], v1[1]); w.w = pk2(v1[2], v1[3]);
;                     *(u32x4*)(rowp + bj * HALF) = w; } }
.Lp1_e0:
	v_lshl_add_u32 v156, s8, 8, v144
	v_lshl_or_b32 v150, s78, 8, v146
	v_ashrrev_i32_e32 v151, 31, v150
	v_mov_b64_e32 v[152:153], s[30:31]
	v_cvt_pk_bf16_f32 v68, v68, v69
	v_cvt_pk_bf16_f32 v69, v70, v71
	v_cvt_pk_bf16_f32 v70, v64, v65
	v_add_u32_e32 v64, 0x80, v156
	v_mad_i64_i32 v[154:155], s[0:1], v156, s77, v[152:153]
	v_lshlrev_b64 v[150:151], 1, v[150:151]
	v_cvt_pk_bf16_f32 v108, v108, v109
	v_cvt_pk_bf16_f32 v109, v110, v111
	v_cvt_pk_bf16_f32 v110, v104, v105
	v_or_b32_e32 v104, 16, v156
	v_mad_i64_i32 v[64:65], s[0:1], v64, s77, v[152:153]
	v_cvt_pk_bf16_f32 v44, v44, v45
	v_cvt_pk_bf16_f32 v45, v46, v47
	v_cvt_pk_bf16_f32 v46, v40, v41
	v_add_u32_e32 v40, 0x90, v156
	v_lshl_add_u64 v[154:155], v[154:155], 0, v[150:151]
	v_cvt_pk_bf16_f32 v111, v106, v107
	v_mad_i64_i32 v[104:105], s[0:1], v104, s77, v[152:153]
	v_cvt_pk_bf16_f32 v92, v92, v93
	v_cvt_pk_bf16_f32 v93, v94, v95
	v_cvt_pk_bf16_f32 v94, v88, v89
	v_or_b32_e32 v88, 32, v156
	v_lshl_add_u64 v[64:65], v[64:65], 0, v[150:151]
	v_cvt_pk_bf16_f32 v47, v42, v43
	v_mad_i64_i32 v[40:41], s[0:1], v40, s77, v[152:153]
	v_cvt_pk_bf16_f32 v28, v28, v29
	v_cvt_pk_bf16_f32 v29, v30, v31
	v_cvt_pk_bf16_f32 v30, v24, v25
	v_add_u32_e32 v24, 0xa0, v156
	global_store_dwordx4 v[154:155], v[108:111], off offset:256 nt
	v_cvt_pk_bf16_f32 v95, v90, v91
	v_mad_i64_i32 v[88:89], s[0:1], v88, s77, v[152:153]
	v_lshl_add_u64 v[108:109], v[104:105], 0, v[150:151]
	v_cvt_pk_bf16_f32 v76, v76, v77
	v_cvt_pk_bf16_f32 v77, v78, v79
	v_cvt_pk_bf16_f32 v78, v72, v73
	v_or_b32_e32 v72, 48, v156
	global_store_dwordx4 v[64:65], v[44:47], off offset:256 nt
	v_cvt_pk_bf16_f32 v31, v26, v27
	v_mad_i64_i32 v[24:25], s[0:1], v24, s77, v[152:153]
	v_lshl_add_u64 v[44:45], v[40:41], 0, v[150:151]
	v_cvt_pk_bf16_f32 v12, v12, v13
	v_cvt_pk_bf16_f32 v13, v14, v15
	v_cvt_pk_bf16_f32 v14, v8, v9
	v_add_u32_e32 v8, 0xb0, v156
	global_store_dwordx4 v[108:109], v[92:95], off offset:256 nt
	v_cvt_pk_bf16_f32 v79, v74, v75
	v_mad_i64_i32 v[72:73], s[0:1], v72, s77, v[152:153]
	v_lshl_add_u64 v[92:93], v[88:89], 0, v[150:151]
	global_store_dwordx4 v[44:45], v[28:31], off offset:256 nt
	v_cvt_pk_bf16_f32 v15, v10, v11
	v_mad_i64_i32 v[8:9], s[0:1], v8, s77, v[152:153]
	v_lshl_add_u64 v[28:29], v[24:25], 0, v[150:151]
	v_cvt_pk_bf16_f32 v124, v124, v125
	v_cvt_pk_bf16_f32 v125, v126, v127
	v_cvt_pk_bf16_f32 v126, v120, v121
	v_cvt_pk_bf16_f32 v127, v122, v123
	v_cvt_pk_bf16_f32 v104, v116, v117
	v_cvt_pk_bf16_f32 v105, v118, v119
	v_cvt_pk_bf16_f32 v106, v112, v113
	v_cvt_pk_bf16_f32 v107, v114, v115
	v_cvt_pk_bf16_f32 v88, v100, v101
	v_cvt_pk_bf16_f32 v89, v102, v103
	v_cvt_pk_bf16_f32 v90, v96, v97
	v_cvt_pk_bf16_f32 v91, v98, v99
	global_store_dwordx4 v[92:93], v[76:79], off offset:256 nt
	v_cvt_pk_bf16_f32 v74, v80, v81
	v_cvt_pk_bf16_f32 v75, v82, v83
	v_lshl_add_u64 v[76:77], v[72:73], 0, v[150:151]
	v_cvt_pk_bf16_f32 v72, v84, v85
	v_cvt_pk_bf16_f32 v73, v86, v87
	v_cvt_pk_bf16_f32 v71, v66, v67
	v_cvt_pk_bf16_f32 v60, v60, v61
	v_cvt_pk_bf16_f32 v61, v62, v63
	v_cvt_pk_bf16_f32 v62, v56, v57
	v_cvt_pk_bf16_f32 v63, v58, v59
	v_cvt_pk_bf16_f32 v40, v52, v53
	v_cvt_pk_bf16_f32 v41, v54, v55
	v_cvt_pk_bf16_f32 v42, v48, v49
	v_cvt_pk_bf16_f32 v43, v50, v51
	v_cvt_pk_bf16_f32 v24, v36, v37
	v_cvt_pk_bf16_f32 v25, v38, v39
	v_cvt_pk_bf16_f32 v26, v32, v33
	v_cvt_pk_bf16_f32 v27, v34, v35
	global_store_dwordx4 v[28:29], v[12:15], off offset:256 nt
	v_cvt_pk_bf16_f32 v10, v16, v17
	v_cvt_pk_bf16_f32 v11, v18, v19
	v_lshl_add_u64 v[12:13], v[8:9], 0, v[150:151]
	v_cvt_pk_bf16_f32 v8, v20, v21
	v_cvt_pk_bf16_f32 v9, v22, v23
	v_cvt_pk_bf16_f32 v4, v4, v5
	v_cvt_pk_bf16_f32 v5, v6, v7
	v_cvt_pk_bf16_f32 v6, v0, v1
	v_cvt_pk_bf16_f32 v7, v2, v3
	s_and_b64 vcc, exec, s[2:3]
	s_mov_b32 s78, s16
	s_mov_b32 s8, s46
	s_mov_b64 s[54:55], s[50:51]
	s_mov_b64 s[52:53], s[48:49]
	global_store_dwordx4 v[154:155], v[124:127], off nt
	global_store_dwordx4 v[108:109], v[104:107], off nt
	global_store_dwordx4 v[92:93], v[88:91], off nt
	global_store_dwordx4 v[76:77], v[72:75], off nt
	global_store_dwordx4 v[76:77], v[68:71], off offset:256 nt
	global_store_dwordx4 v[64:65], v[60:63], off nt
	global_store_dwordx4 v[44:45], v[40:43], off nt
	global_store_dwordx4 v[28:29], v[24:27], off nt
	global_store_dwordx4 v[12:13], v[8:11], off nt
	global_store_dwordx4 v[12:13], v[4:7], off offset:256 nt
	s_cmpk_le_u32 s33, 0xff
	s_cbranch_scc1 .Lp1_e1
	s_barrier
.Lp1_e1:
	s_cbranch_vccz .LBB0_110
	s_waitcnt vmcnt(0)
	s_cmpk_gt_u32 s33, 0xff
	s_cbranch_scc1 .LBB0_117
	s_barrier
